# v060 + saddr-form LDS-DMA without VALU address math in the FFN-in loop LOAD segments
# speedup vs baseline: 1.0039x; 1.0024x over previous
.LBB0_1565:
	s_add_u32 s20, s18, 0xfff80080
	s_addc_u32 s21, s19, -1
	s_cmp_eq_u32 s53, 28
	s_cselect_b32 s23, s9, s21
	s_cselect_b32 s22, s15, s20
	s_cselect_b32 s21, s7, s52
	s_cselect_b32 s20, s50, s51
	s_add_i32 s54, 0, 0x10000
	s_add_i32 s56, 0, 0x14000
	v_add_u32_e32 v158, 0x10000, v160
	ds_read_b128 v[164:167], v158
	ds_read_b128 v[168:171], v158 offset:1024
	ds_read_b128 v[172:175], v158 offset:2048
	ds_read_b128 v[176:179], v158 offset:3072
	ds_read_b128 v[180:183], v158 offset:16384
	ds_read_b128 v[184:187], v158 offset:17408
	ds_read_b128 v[188:191], v158 offset:18432
	ds_read_b128 v[192:195], v158 offset:19456
	s_add_i32 m0, s17, 0xc000
	ds_read_b128 v[196:199], v162
	ds_read_b128 v[200:203], v162 offset:1024
	ds_read_b128 v[204:207], v162 offset:2048
	ds_read_b128 v[220:223], v162 offset:3072
	ds_read_b128 v[224:227], v162 offset:4096
	ds_read_b128 v[228:231], v162 offset:5120
	ds_read_b128 v[232:235], v162 offset:6144
	ds_read_b128 v[236:239], v162 offset:7168
	global_load_lds_dwordx4 v154, s[18:19]
	s_add_i32 m0, s17, 0xe000
	s_nop 0
	global_load_lds_dwordx4 v156, s[18:19]
	s_waitcnt vmcnt(8)
	s_waitcnt lgkmcnt(0)
	s_barrier
	s_setprio 1
	s_waitcnt lgkmcnt(0)
	v_mfma_f32_16x16x32_bf16 v[122:125], v[164:167], v[196:199], v[122:125]
	v_mfma_f32_16x16x32_bf16 v[114:117], v[172:175], v[196:199], v[114:117]
	v_mfma_f32_16x16x32_bf16 v[106:109], v[164:167], v[204:207], v[106:109]
	v_mfma_f32_16x16x32_bf16 v[98:101], v[172:175], v[204:207], v[98:101]
	v_mfma_f32_16x16x32_bf16 v[90:93], v[164:167], v[224:227], v[90:93]
	v_mfma_f32_16x16x32_bf16 v[82:85], v[172:175], v[224:227], v[82:85]
	v_mfma_f32_16x16x32_bf16 v[74:77], v[164:167], v[232:235], v[74:77]
	v_mfma_f32_16x16x32_bf16 v[66:69], v[172:175], v[232:235], v[66:69]
	v_mfma_f32_16x16x32_bf16 v[122:125], v[168:171], v[200:203], v[122:125]
	v_mfma_f32_16x16x32_bf16 v[114:117], v[176:179], v[200:203], v[114:117]
	v_mfma_f32_16x16x32_bf16 v[106:109], v[168:171], v[220:223], v[106:109]
	v_mfma_f32_16x16x32_bf16 v[98:101], v[176:179], v[220:223], v[98:101]
	v_mfma_f32_16x16x32_bf16 v[90:93], v[168:171], v[228:231], v[90:93]
	v_mfma_f32_16x16x32_bf16 v[82:85], v[176:179], v[228:231], v[82:85]
	v_mfma_f32_16x16x32_bf16 v[74:77], v[168:171], v[236:239], v[74:77]
	v_mfma_f32_16x16x32_bf16 v[66:69], v[176:179], v[236:239], v[66:69]
	s_setprio 0
	s_setprio 1
	v_mfma_f32_16x16x32_bf16 v[126:129], v[180:183], v[196:199], v[126:129]
	v_mfma_f32_16x16x32_bf16 v[118:121], v[188:191], v[196:199], v[118:121]
	v_mfma_f32_16x16x32_bf16 v[110:113], v[180:183], v[204:207], v[110:113]
	v_mfma_f32_16x16x32_bf16 v[102:105], v[188:191], v[204:207], v[102:105]
	v_mfma_f32_16x16x32_bf16 v[94:97], v[180:183], v[224:227], v[94:97]
	v_mfma_f32_16x16x32_bf16 v[86:89], v[188:191], v[224:227], v[86:89]
	v_mfma_f32_16x16x32_bf16 v[78:81], v[180:183], v[232:235], v[78:81]
	v_mfma_f32_16x16x32_bf16 v[70:73], v[188:191], v[232:235], v[70:73]
	v_mfma_f32_16x16x32_bf16 v[126:129], v[184:187], v[200:203], v[126:129]
	v_mfma_f32_16x16x32_bf16 v[118:121], v[192:195], v[200:203], v[118:121]
	v_mfma_f32_16x16x32_bf16 v[110:113], v[184:187], v[220:223], v[110:113]
	v_mfma_f32_16x16x32_bf16 v[102:105], v[192:195], v[220:223], v[102:105]
	v_mfma_f32_16x16x32_bf16 v[94:97], v[184:187], v[228:231], v[94:97]
	v_mfma_f32_16x16x32_bf16 v[86:89], v[192:195], v[228:231], v[86:89]
	v_mfma_f32_16x16x32_bf16 v[78:81], v[184:187], v[236:239], v[78:81]
	v_mfma_f32_16x16x32_bf16 v[70:73], v[192:195], v[236:239], v[70:73]
	s_setprio 0
	s_barrier
	s_add_i32 s54, s54, s41
	s_mov_b32 m0, s54
	ds_read_b128 v[196:199], v162 offset:16384
	ds_read_b128 v[200:203], v162 offset:17408
	ds_read_b128 v[204:207], v162 offset:18432
	ds_read_b128 v[220:223], v162 offset:19456
	ds_read_b128 v[224:227], v162 offset:20480
	ds_read_b128 v[228:231], v162 offset:21504
	ds_read_b128 v[232:235], v162 offset:22528
	ds_read_b128 v[236:239], v162 offset:23552
	global_load_lds_dwordx4 v0, s[20:21]
	s_add_i32 m0, s54, 0x2000
	s_add_u32 s54, s20, 0x80000
	s_addc_u32 s55, s21, 0
	s_add_i32 s56, s56, s41
	global_load_lds_dwordx4 v130, s[20:21]
	s_mov_b32 m0, s56
	s_nop 0
	global_load_lds_dwordx4 v0, s[54:55]
	s_add_i32 m0, s56, 0x2000
	s_nop 0
	global_load_lds_dwordx4 v130, s[54:55]
	s_mov_b32 m0, s17
	s_nop 0
	global_load_lds_dwordx4 v134, s[22:23]
	s_mov_b32 m0, s43
	s_nop 0
	global_load_lds_dwordx4 v132, s[22:23]
	s_waitcnt vmcnt(8)
	s_waitcnt lgkmcnt(0)
	s_barrier
	s_setprio 1
	s_waitcnt lgkmcnt(0)
	v_mfma_f32_16x16x32_bf16 v[58:61], v[164:167], v[196:199], v[58:61]
	v_mfma_f32_16x16x32_bf16 v[50:53], v[172:175], v[196:199], v[50:53]
	v_mfma_f32_16x16x32_bf16 v[42:45], v[164:167], v[204:207], v[42:45]
	v_mfma_f32_16x16x32_bf16 v[34:37], v[172:175], v[204:207], v[34:37]
	v_mfma_f32_16x16x32_bf16 v[26:29], v[164:167], v[224:227], v[26:29]
	v_mfma_f32_16x16x32_bf16 v[18:21], v[172:175], v[224:227], v[18:21]
	v_mfma_f32_16x16x32_bf16 v[10:13], v[164:167], v[232:235], v[10:13]
	v_mfma_f32_16x16x32_bf16 v[2:5], v[172:175], v[232:235], v[2:5]
	v_mfma_f32_16x16x32_bf16 v[58:61], v[168:171], v[200:203], v[58:61]
	v_mfma_f32_16x16x32_bf16 v[50:53], v[176:179], v[200:203], v[50:53]
	v_mfma_f32_16x16x32_bf16 v[42:45], v[168:171], v[220:223], v[42:45]
	v_mfma_f32_16x16x32_bf16 v[34:37], v[176:179], v[220:223], v[34:37]
	v_mfma_f32_16x16x32_bf16 v[26:29], v[168:171], v[228:231], v[26:29]
	v_mfma_f32_16x16x32_bf16 v[18:21], v[176:179], v[228:231], v[18:21]
	v_mfma_f32_16x16x32_bf16 v[10:13], v[168:171], v[236:239], v[10:13]
	v_mfma_f32_16x16x32_bf16 v[2:5], v[176:179], v[236:239], v[2:5]
	s_setprio 0
	s_setprio 1
	v_mfma_f32_16x16x32_bf16 v[62:65], v[180:183], v[196:199], v[62:65]
	v_mfma_f32_16x16x32_bf16 v[54:57], v[188:191], v[196:199], v[54:57]
	v_mfma_f32_16x16x32_bf16 v[46:49], v[180:183], v[204:207], v[46:49]
	v_mfma_f32_16x16x32_bf16 v[38:41], v[188:191], v[204:207], v[38:41]
	v_mfma_f32_16x16x32_bf16 v[30:33], v[180:183], v[224:227], v[30:33]
	v_mfma_f32_16x16x32_bf16 v[22:25], v[188:191], v[224:227], v[22:25]
	v_mfma_f32_16x16x32_bf16 v[14:17], v[180:183], v[232:235], v[14:17]
	v_mfma_f32_16x16x32_bf16 v[6:9], v[188:191], v[232:235], v[6:9]
	v_mfma_f32_16x16x32_bf16 v[62:65], v[184:187], v[200:203], v[62:65]
	v_mfma_f32_16x16x32_bf16 v[54:57], v[192:195], v[200:203], v[54:57]
	v_mfma_f32_16x16x32_bf16 v[46:49], v[184:187], v[220:223], v[46:49]
	v_mfma_f32_16x16x32_bf16 v[38:41], v[192:195], v[220:223], v[38:41]
	v_mfma_f32_16x16x32_bf16 v[30:33], v[184:187], v[228:231], v[30:33]
	v_mfma_f32_16x16x32_bf16 v[22:25], v[192:195], v[228:231], v[22:25]
	v_mfma_f32_16x16x32_bf16 v[14:17], v[184:187], v[236:239], v[14:17]
	v_mfma_f32_16x16x32_bf16 v[6:9], v[192:195], v[236:239], v[6:9]
	s_setprio 0
	s_barrier
	ds_read_b128 v[164:167], v158 offset:32768
	ds_read_b128 v[168:171], v158 offset:33792
	ds_read_b128 v[172:175], v158 offset:34816
	ds_read_b128 v[176:179], v158 offset:35840
	ds_read_b128 v[180:183], v158 offset:49152
	ds_read_b128 v[184:187], v158 offset:50176
	ds_read_b128 v[188:191], v158 offset:51200
	ds_read_b128 v[192:195], v158 offset:52224
	s_add_i32 s54, 0, 0x18000
	s_add_i32 s55, 0, 0x1c000
	s_add_u32 s22, s22, 0x80000
	s_addc_u32 s23, s23, 0
	s_mov_b32 m0, s44
	ds_read_b128 v[196:199], v162 offset:32768
	ds_read_b128 v[200:203], v162 offset:33792
	ds_read_b128 v[204:207], v162 offset:34816
	ds_read_b128 v[220:223], v162 offset:35840
	ds_read_b128 v[224:227], v162 offset:36864
	ds_read_b128 v[228:231], v162 offset:37888
	ds_read_b128 v[232:235], v162 offset:38912
	ds_read_b128 v[236:239], v162 offset:39936
	global_load_lds_dwordx4 v134, s[22:23]
	s_mov_b32 m0, s45
	s_nop 0
	global_load_lds_dwordx4 v132, s[22:23]
	s_waitcnt vmcnt(8)
	s_waitcnt lgkmcnt(0)
	s_barrier
	s_setprio 1
	s_waitcnt lgkmcnt(0)
	v_mfma_f32_16x16x32_bf16 v[122:125], v[164:167], v[196:199], v[122:125]
	v_mfma_f32_16x16x32_bf16 v[114:117], v[172:175], v[196:199], v[114:117]
	v_mfma_f32_16x16x32_bf16 v[106:109], v[164:167], v[204:207], v[106:109]
	v_mfma_f32_16x16x32_bf16 v[98:101], v[172:175], v[204:207], v[98:101]
	v_mfma_f32_16x16x32_bf16 v[90:93], v[164:167], v[224:227], v[90:93]
	v_mfma_f32_16x16x32_bf16 v[82:85], v[172:175], v[224:227], v[82:85]
	v_mfma_f32_16x16x32_bf16 v[74:77], v[164:167], v[232:235], v[74:77]
	v_mfma_f32_16x16x32_bf16 v[66:69], v[172:175], v[232:235], v[66:69]
	v_mfma_f32_16x16x32_bf16 v[122:125], v[168:171], v[200:203], v[122:125]
	v_mfma_f32_16x16x32_bf16 v[114:117], v[176:179], v[200:203], v[114:117]
	v_mfma_f32_16x16x32_bf16 v[106:109], v[168:171], v[220:223], v[106:109]
	v_mfma_f32_16x16x32_bf16 v[98:101], v[176:179], v[220:223], v[98:101]
	v_mfma_f32_16x16x32_bf16 v[90:93], v[168:171], v[228:231], v[90:93]
	v_mfma_f32_16x16x32_bf16 v[82:85], v[176:179], v[228:231], v[82:85]
	v_mfma_f32_16x16x32_bf16 v[74:77], v[168:171], v[236:239], v[74:77]
	v_mfma_f32_16x16x32_bf16 v[66:69], v[176:179], v[236:239], v[66:69]
	s_setprio 0
	s_setprio 1
	v_mfma_f32_16x16x32_bf16 v[126:129], v[180:183], v[196:199], v[126:129]
	v_mfma_f32_16x16x32_bf16 v[118:121], v[188:191], v[196:199], v[118:121]
	v_mfma_f32_16x16x32_bf16 v[110:113], v[180:183], v[204:207], v[110:113]
	v_mfma_f32_16x16x32_bf16 v[102:105], v[188:191], v[204:207], v[102:105]
	v_mfma_f32_16x16x32_bf16 v[94:97], v[180:183], v[224:227], v[94:97]
	v_mfma_f32_16x16x32_bf16 v[86:89], v[188:191], v[224:227], v[86:89]
	v_mfma_f32_16x16x32_bf16 v[78:81], v[180:183], v[232:235], v[78:81]
	v_mfma_f32_16x16x32_bf16 v[70:73], v[188:191], v[232:235], v[70:73]
	v_mfma_f32_16x16x32_bf16 v[126:129], v[184:187], v[200:203], v[126:129]
	v_mfma_f32_16x16x32_bf16 v[118:121], v[192:195], v[200:203], v[118:121]
	v_mfma_f32_16x16x32_bf16 v[110:113], v[184:187], v[220:223], v[110:113]
	v_mfma_f32_16x16x32_bf16 v[102:105], v[192:195], v[220:223], v[102:105]
	v_mfma_f32_16x16x32_bf16 v[94:97], v[184:187], v[228:231], v[94:97]
	v_mfma_f32_16x16x32_bf16 v[86:89], v[192:195], v[228:231], v[86:89]
	v_mfma_f32_16x16x32_bf16 v[78:81], v[184:187], v[236:239], v[78:81]
	v_mfma_f32_16x16x32_bf16 v[70:73], v[192:195], v[236:239], v[70:73]
	s_setprio 0
	s_barrier
	s_add_u32 vcc_lo, s22, 0xfff80080
	s_addc_u32 vcc_hi, s23, -1
	s_add_i32 s22, s54, s41
	s_add_i32 s56, s55, s41
	s_add_u32 s54, s20, 0x80
	s_addc_u32 s55, s21, 0
	s_add_u32 s20, s20, 0x80080
	s_addc_u32 s21, s21, 0
	s_mov_b32 m0, s22
	ds_read_b128 v[196:199], v162 offset:49152
	ds_read_b128 v[200:203], v162 offset:50176
	ds_read_b128 v[204:207], v162 offset:51200
	ds_read_b128 v[220:223], v162 offset:52224
	ds_read_b128 v[224:227], v162 offset:53248
	ds_read_b128 v[228:231], v162 offset:54272
	ds_read_b128 v[232:235], v162 offset:55296
	ds_read_b128 v[236:239], v162 offset:56320
	global_load_lds_dwordx4 v0, s[54:55]
	s_add_i32 m0, s22, 0x2000
	s_nop 0
	global_load_lds_dwordx4 v130, s[54:55]
	s_mov_b32 m0, s56
	s_nop 0
	global_load_lds_dwordx4 v0, s[20:21]
	s_add_i32 m0, s56, 0x2000
	s_nop 0
	global_load_lds_dwordx4 v130, s[20:21]
	s_mov_b32 m0, s46
	s_nop 0
	global_load_lds_dwordx4 v134, vcc
	s_mov_b32 m0, s47
	s_nop 0
	global_load_lds_dwordx4 v132, vcc
	s_waitcnt vmcnt(8)
	s_waitcnt lgkmcnt(0)
	s_barrier
	s_setprio 1
	s_waitcnt lgkmcnt(0)
	v_mfma_f32_16x16x32_bf16 v[58:61], v[164:167], v[196:199], v[58:61]
	v_mfma_f32_16x16x32_bf16 v[50:53], v[172:175], v[196:199], v[50:53]
	v_mfma_f32_16x16x32_bf16 v[42:45], v[164:167], v[204:207], v[42:45]
	v_mfma_f32_16x16x32_bf16 v[34:37], v[172:175], v[204:207], v[34:37]
	v_mfma_f32_16x16x32_bf16 v[26:29], v[164:167], v[224:227], v[26:29]
	v_mfma_f32_16x16x32_bf16 v[18:21], v[172:175], v[224:227], v[18:21]
	v_mfma_f32_16x16x32_bf16 v[10:13], v[164:167], v[232:235], v[10:13]
	v_mfma_f32_16x16x32_bf16 v[2:5], v[172:175], v[232:235], v[2:5]
	v_mfma_f32_16x16x32_bf16 v[58:61], v[168:171], v[200:203], v[58:61]
	v_mfma_f32_16x16x32_bf16 v[50:53], v[176:179], v[200:203], v[50:53]
	v_mfma_f32_16x16x32_bf16 v[42:45], v[168:171], v[220:223], v[42:45]
	v_mfma_f32_16x16x32_bf16 v[34:37], v[176:179], v[220:223], v[34:37]
	v_mfma_f32_16x16x32_bf16 v[26:29], v[168:171], v[228:231], v[26:29]
	v_mfma_f32_16x16x32_bf16 v[18:21], v[176:179], v[228:231], v[18:21]
	v_mfma_f32_16x16x32_bf16 v[10:13], v[168:171], v[236:239], v[10:13]
	v_mfma_f32_16x16x32_bf16 v[2:5], v[176:179], v[236:239], v[2:5]
	s_setprio 0
	s_setprio 1
	v_mfma_f32_16x16x32_bf16 v[62:65], v[180:183], v[196:199], v[62:65]
	v_mfma_f32_16x16x32_bf16 v[54:57], v[188:191], v[196:199], v[54:57]
	v_mfma_f32_16x16x32_bf16 v[46:49], v[180:183], v[204:207], v[46:49]
	v_mfma_f32_16x16x32_bf16 v[38:41], v[188:191], v[204:207], v[38:41]
	v_mfma_f32_16x16x32_bf16 v[30:33], v[180:183], v[224:227], v[30:33]
	v_mfma_f32_16x16x32_bf16 v[22:25], v[188:191], v[224:227], v[22:25]
	v_mfma_f32_16x16x32_bf16 v[14:17], v[180:183], v[232:235], v[14:17]
	v_mfma_f32_16x16x32_bf16 v[6:9], v[188:191], v[232:235], v[6:9]
	v_mfma_f32_16x16x32_bf16 v[62:65], v[184:187], v[200:203], v[62:65]
	v_mfma_f32_16x16x32_bf16 v[54:57], v[192:195], v[200:203], v[54:57]
	v_mfma_f32_16x16x32_bf16 v[46:49], v[184:187], v[220:223], v[46:49]
	v_mfma_f32_16x16x32_bf16 v[38:41], v[192:195], v[220:223], v[38:41]
	v_mfma_f32_16x16x32_bf16 v[30:33], v[184:187], v[228:231], v[30:33]
	v_mfma_f32_16x16x32_bf16 v[22:25], v[192:195], v[228:231], v[22:25]
	v_mfma_f32_16x16x32_bf16 v[14:17], v[184:187], v[236:239], v[14:17]
	v_mfma_f32_16x16x32_bf16 v[6:9], v[192:195], v[236:239], v[6:9]
	s_setprio 0
	s_barrier
	s_add_i32 s53, s53, 2
	s_add_u32 s18, s18, 0x100
	s_addc_u32 s19, s19, 0
	s_add_u32 s51, s51, 0x100
	s_addc_u32 s52, s52, 0
	s_cmp_gt_u32 s53, 29
	s_cbranch_scc0 .LBB0_1565
